# stack + next-unit decode: division by the group size (always 8) as a shift in FFN-up and QKV unit loops
# baseline (speedup 1.0000x reference)
.LBB0_164:
	s_add_i32 s14, s14, 1
	v_readlane_b32 s4, v254, 0
	s_mul_i32 s2, s14, s76
	s_mov_b32 s28, s4
	s_mul_hi_u32 s4, s14, s4
	s_add_i32 s4, s4, s2
	s_mul_i32 s2, s14, s28
	s_add_u32 s28, s2, s91
	s_addc_u32 s29, s4, s51
	v_readlane_b32 s5, v254, 1
	v_cmp_ge_i64_e32 vcc, s[28:29], v[140:141]
	v_cmp_lt_i64_e64 s[4:5], s[28:29], v[140:141]
	s_cbranch_vccnz .LBB0_166
	s_ashr_i32 s2, s28, 31
	s_lshr_b32 s2, s2, 29
	s_add_i32 s2, s28, s2
	s_ashr_i32 s15, s2, 3
	s_and_b32 s2, s2, -8
	s_sub_i32 s2, s28, s2
	s_cmp_lt_i32 s2, 0
	s_cselect_b32 s24, s68, s53
	s_mul_i32 s2, s24, s2
	s_add_i32 s2, s2, s15
	s_mul_hi_i32 s15, s2, 0x2e8ba2e9
	s_lshr_b32 s24, s15, 31
	s_ashr_i32 s15, s15, 5
	s_add_i32 s15, s15, s24
	s_lshl_b32 s25, s15, 3
	s_sub_i32 s24, s52, s25
	s_min_i32 s26, s24, 8
	s_mulk_i32 s15, 0xb0
	s_sub_i32 s2, s2, s15
	s_ashr_i32 s24, s2, 3
	s_mul_i32 s15, s24, s26
	s_sub_i32 s2, s2, s15
	s_add_i32 s26, s2, s25

.LBB0_705:
	s_add_i32 s4, s4, 1
	v_readlane_b32 s8, v254, 0
	s_mul_i32 s2, s4, s76
	s_mov_b32 s26, s8
	s_mul_hi_u32 s8, s4, s8
	s_add_i32 s8, s8, s2
	s_mul_i32 s2, s4, s26
	s_add_u32 s26, s2, s91
	s_addc_u32 s27, s8, s51
	v_mov_b64_e32 v[2:3], s[66:67]
	v_readlane_b32 s9, v254, 1
	v_cmp_ge_i64_e32 vcc, s[26:27], v[2:3]
	v_cmp_lt_i64_e64 s[8:9], s[26:27], v[2:3]
	s_cbranch_vccnz .LBB0_707
	s_ashr_i32 s2, s26, 31
	s_lshr_b32 s2, s2, 29
	s_add_i32 s2, s26, s2
	s_ashr_i32 s11, s2, 3
	s_and_b32 s2, s2, -8
	s_sub_i32 s2, s26, s2
	s_lshr_b32 s13, s2, 31
	s_or_b32 s13, s5, s13
	s_mul_i32 s2, s13, s2
	s_add_i32 s2, s2, s11
	s_abs_i32 s13, s2
	s_mul_hi_u32 s22, s13, s12
	s_mul_i32 s23, s22, s53
	s_sub_i32 s13, s13, s23
	s_ashr_i32 s11, s2, 31
	s_add_i32 s23, s22, 1
	s_sub_i32 s24, s13, s53
	s_cmp_ge_u32 s13, s53
	s_cselect_b32 s22, s23, s22
	s_cselect_b32 s13, s24, s13
	s_add_i32 s23, s22, 1
	s_cmp_ge_u32 s13, s53
	s_cselect_b32 s13, s23, s22
	s_xor_b32 s13, s13, s11
	s_sub_i32 s11, s13, s11
	s_lshl_b32 s13, s11, 3
	s_sub_i32 s22, 0x48, s13
	s_min_i32 s23, s22, 8
	s_mul_i32 s11, s11, s53
	s_sub_i32 s2, s2, s11
	s_ashr_i32 s22, s2, 3
	s_mul_i32 s11, s22, s23
	s_sub_i32 s2, s2, s11
	s_add_i32 s24, s2, s13
